# v60 + XCD-local barriers at seams 3,4,6,8,9 (producer and consumer on the same XCD; runtime placement guard, falls back to grid barrier) + P9 row-panel mirror inside the batch
# speedup vs baseline: 1.0104x; 1.0104x over previous
; #define LAS __attribute__((address_space(3)))
; __device__ __forceinline__ unsigned xb_add(unsigned* p, unsigned v) { return __hip_atomic_fetch_add(p, v, __ATOMIC_RELAXED, __HIP_MEMORY_SCOPE_AGENT); }
; __device__ __forceinline__ unsigned xb_xcc_id() { return (unsigned)__builtin_amdgcn_s_getreg((3 << 11) | 20) & 0xFu; }
; __device__ __forceinline__ XcdBarrier xcd_barrier_post(unsigned* bar, volatile LAS unsigned* st, bool leader) {
;     XcdBarrier b; b.bar = bar; b.x = xb_xcc_id(); b.st = st;
;     if (leader) (void)xb_add(&bar[XB_XCNT(b.x)], 1u);
;     return b;
; }
.LBB0_7:
	s_getreg_b32 s2, hwreg(HW_REG_XCC_ID, 0, 4)
	s_and_b32 s92, s2, 15
	s_and_saveexec_b64 s[12:13], s[14:15]
	s_cbranch_execz .LBB0_10
	s_mov_b64 s[14:15], exec
	v_mbcnt_lo_u32_b32 v2, s14, 0
	v_mbcnt_hi_u32_b32 v2, s15, v2
	v_cmp_eq_u32_e32 vcc, 0, v2
	s_and_b64 s[2:3], exec, vcc
	s_mov_b64 exec, s[2:3]
	s_cbranch_execz .LBB0_10
	s_lshl_b32 s2, s92, 8
	s_bcnt1_i32_b64 s3, s[14:15]
	v_mov_b32_e32 v2, s2
	v_mov_b32_e32 v3, s3
	v_readlane_b32 s2, v254, 2
	v_readlane_b32 s3, v254, 3
	s_nop 4
	global_atomic_add v2, v3, s[2:3] offset:1024
	s_and_b32 s14, s88, 7
	s_lshl_b32 s14, s14, 2
	s_lshl_b32 s15, 1, s92
	s_cmp_lg_u32 s82, 0x100
	s_cselect_b32 s15, 0xffff, s15
	v_mov_b32_e32 v2, s14
	v_mov_b32_e32 v3, s15
	global_atomic_or v2, v3, s[2:3] offset:768

; __device__ __forceinline__ unsigned xb_ld(unsigned* p)              { return __hip_atomic_load(p, __ATOMIC_RELAXED, __HIP_MEMORY_SCOPE_AGENT); }
; __device__ __forceinline__ unsigned xb_add(unsigned* p, unsigned v) { return __hip_atomic_fetch_add(p, v, __ATOMIC_RELAXED, __HIP_MEMORY_SCOPE_AGENT); }
; #define XB_SPIN(cond, bar) do { unsigned _sp = 0; while (cond) { __builtin_amdgcn_s_sleep(1); \
;     if ((++_sp & 255u) == 0u) { if (xb_ld(&(bar)[XB_TMO])) break; if (_sp > XB_SPIN_CAP) { atomicAdd(&(bar)[XB_TMO], 1u); break; } } } } while (0)
; __device__ __forceinline__ void xcd_barrier(const XcdBarrier& b, bool leader) {
;     asm volatile("s_waitcnt vmcnt(0)" ::: "memory");
;     __syncthreads();
;     if (leader) {
;         unsigned* bar = b.bar;
;         __builtin_amdgcn_s_waitcnt(0);
;         unsigned nloc = b.st[0], nx = b.st[1];
;         if (nloc == 0u) { xcd_barrier_complete(bar, b.x, nloc, nx); b.st[0] = nloc; b.st[1] = nx; }
;         const unsigned old = xb_add(&bar[XB_XSUB(b.x)], 1u);
;         const unsigned gen = old / nloc;
;         if (old + 1u == (gen + 1u) * nloc) {
;             __builtin_amdgcn_fence(__ATOMIC_RELEASE, "agent");
;             asm volatile("s_waitcnt vmcnt(0)" ::: "memory");
;             const unsigned og = xb_add(&bar[XB_TOP], 1u);
;             const unsigned tg = og / nx;
;             if (og + 1u == (tg + 1u) * nx) xb_add(&bar[XB_TOPGEN], 1u);
;             else XB_SPIN(xb_ld(&bar[XB_TOPGEN]) == tg, bar);
;             __builtin_amdgcn_fence(__ATOMIC_ACQUIRE, "agent");
;             xb_add(&bar[XB_XGEN(b.x)], 1u);
;             asm volatile("s_waitcnt vmcnt(0)" ::: "memory");
;         } else {
;             XB_SPIN(xb_ld(&bar[XB_XGEN(b.x)]) == gen, bar);
;             __builtin_amdgcn_fence(__ATOMIC_ACQUIRE, "agent");
;             asm volatile("s_waitcnt vmcnt(0)" ::: "memory");
;         }
;     }
;     __syncthreads();
; }
.LBB0_851:
	s_waitcnt vmcnt(0)
	s_waitcnt lgkmcnt(0)
	s_barrier
	s_and_saveexec_b64 s[4:5], s[6:7]
	s_cbranch_execz .LBB0_899
	v_readlane_b32 s8, v254, 2
	v_readlane_b32 s9, v254, 3
	s_and_b32 s2, s88, 7
	s_lshl_b32 s2, s2, 8
	s_add_u32 s2, s8, s2
	s_addc_u32 s3, s9, 0
	v_mov_b32_e32 v0, 0
	v_mov_b32_e32 v1, 1
	v_mov_b32_e32 v5, 0x1400
	global_load_dwordx4 v[6:9], v0, s[8:9] offset:768 sc1
	global_load_dwordx4 v[10:13], v0, s[8:9] offset:784 sc1
	global_atomic_add v3, v5, v1, s[2:3] offset:128 sc0
	s_waitcnt vmcnt(0)
	v_add_u32_e32 v14, -1, v6
	v_and_b32_e32 v2, v14, v6
	v_add_u32_e32 v14, -1, v7
	v_and_or_b32 v2, v14, v7, v2
	v_add_u32_e32 v14, -1, v8
	v_and_or_b32 v2, v14, v8, v2
	v_add_u32_e32 v14, -1, v9
	v_and_or_b32 v2, v14, v9, v2
	v_add_u32_e32 v14, -1, v10
	v_and_or_b32 v2, v14, v10, v2
	v_add_u32_e32 v14, -1, v11
	v_and_or_b32 v2, v14, v11, v2
	v_add_u32_e32 v14, -1, v12
	v_and_or_b32 v2, v14, v12, v2
	v_add_u32_e32 v14, -1, v13
	v_and_or_b32 v2, v14, v13, v2
	v_cmp_ne_u32_e32 vcc, 0, v2
	s_cbranch_vccnz .Lmy_glob_k3
	v_and_b32_e32 v4, 0xffffffe0, v3
	v_add_u32_e32 v4, 32, v4
	v_add_u32_e32 v3, 1, v3
	v_cmp_eq_u32_e32 vcc, v3, v4
	s_cbranch_vccnz .Lmy_done_k3
	s_mov_b32 s10, 0
.Lmy_spin_k3:
	s_sleep 1
	global_load_dword v2, v5, s[2:3] offset:128 sc1
	s_add_i32 s10, s10, 1
	s_cmp_gt_u32 s10, 0x100000
	s_cbranch_scc1 .Lmy_done_k3
	s_waitcnt vmcnt(0)
	v_sub_u32_e32 v2, v2, v4
	v_cmp_gt_i32_e32 vcc, 0, v2
	s_cbranch_vccnz .Lmy_spin_k3
.Lmy_done_k3:
	s_waitcnt vmcnt(0)
	buffer_inv sc1
	s_waitcnt vmcnt(0)
	s_branch .LBB0_899
.Lmy_glob_k3:
	s_add_i32 s2, 0, 0x20400
	v_mov_b32_e32 v0, s2
	s_waitcnt vmcnt(0) expcnt(0) lgkmcnt(0)
	ds_read_b32 v2, v0
	s_add_i32 s2, 0, 0x20404
	v_mov_b32_e32 v0, s2
	ds_read_b32 v0, v0
	s_waitcnt lgkmcnt(1)
	v_cmp_ne_u32_e32 vcc, 0, v2
	s_cbranch_vccnz .LBB0_867
	v_readlane_b32 s6, v254, 0
	v_readlane_b32 s7, v254, 1
	s_load_dwordx2 s[2:3], s[6:7], 0x4
	s_add_u32 s6, s72, 0x310200
	s_addc_u32 s7, s73, 0
	s_add_u32 s8, s72, 0x310400
	s_addc_u32 s9, s73, 0
	s_add_u32 s10, s72, 0x310500
	s_addc_u32 s11, s73, 0
	s_add_u32 s12, s72, 0x310600
	s_addc_u32 s13, s73, 0
	s_add_u32 s14, s72, 0x310700
	s_addc_u32 s15, s73, 0
	s_add_u32 s16, s72, 0x310800
	s_addc_u32 s17, s73, 0
	s_add_u32 s18, s72, 0x310900
	s_addc_u32 s19, s73, 0
	s_add_u32 s22, s72, 0x310a00
	s_addc_u32 s23, s73, 0
	s_add_u32 s24, s72, 0x310b00
	s_addc_u32 s25, s73, 0
	s_add_u32 s26, s72, 0x310c00
	s_addc_u32 s27, s73, 0
	s_add_u32 s28, s72, 0x310d00
	s_addc_u32 s29, s73, 0
	s_add_u32 s30, s72, 0x310e00
	s_addc_u32 s31, s73, 0
	s_add_u32 s34, s72, 0x310f00
	s_addc_u32 s35, s73, 0
	s_add_u32 s36, s72, 0x311000
	s_addc_u32 s37, s73, 0
	s_add_u32 s38, s72, 0x311100
	s_addc_u32 s39, s73, 0
	s_add_u32 s40, s72, 0x311200
	s_addc_u32 s41, s73, 0
	s_waitcnt lgkmcnt(0)
	s_mul_i32 s2, s2, s82
	s_add_u32 s42, s72, 0x311300
	s_mul_i32 s2, s2, s3
	s_addc_u32 s43, s73, 0
	s_mov_b32 s3, 1
	v_mov_b32_e32 v16, 0
	s_branch .LBB0_855

; __device__ __forceinline__ unsigned xb_ld(unsigned* p)              { return __hip_atomic_load(p, __ATOMIC_RELAXED, __HIP_MEMORY_SCOPE_AGENT); }
; __device__ __forceinline__ unsigned xb_add(unsigned* p, unsigned v) { return __hip_atomic_fetch_add(p, v, __ATOMIC_RELAXED, __HIP_MEMORY_SCOPE_AGENT); }
; #define XB_SPIN(cond, bar) do { unsigned _sp = 0; while (cond) { __builtin_amdgcn_s_sleep(1); \
;     if ((++_sp & 255u) == 0u) { if (xb_ld(&(bar)[XB_TMO])) break; if (_sp > XB_SPIN_CAP) { atomicAdd(&(bar)[XB_TMO], 1u); break; } } } } while (0)
; __device__ __forceinline__ void xcd_barrier(const XcdBarrier& b, bool leader) {
;     asm volatile("s_waitcnt vmcnt(0)" ::: "memory");
;     __syncthreads();
;     if (leader) {
;         unsigned* bar = b.bar;
;         __builtin_amdgcn_s_waitcnt(0);
;         unsigned nloc = b.st[0], nx = b.st[1];
;         if (nloc == 0u) { xcd_barrier_complete(bar, b.x, nloc, nx); b.st[0] = nloc; b.st[1] = nx; }
;         const unsigned old = xb_add(&bar[XB_XSUB(b.x)], 1u);
;         const unsigned gen = old / nloc;
;         if (old + 1u == (gen + 1u) * nloc) {
;             __builtin_amdgcn_fence(__ATOMIC_RELEASE, "agent");
;             asm volatile("s_waitcnt vmcnt(0)" ::: "memory");
;             const unsigned og = xb_add(&bar[XB_TOP], 1u);
;             const unsigned tg = og / nx;
;             if (og + 1u == (tg + 1u) * nx) xb_add(&bar[XB_TOPGEN], 1u);
;             else XB_SPIN(xb_ld(&bar[XB_TOPGEN]) == tg, bar);
;             __builtin_amdgcn_fence(__ATOMIC_ACQUIRE, "agent");
;             xb_add(&bar[XB_XGEN(b.x)], 1u);
;             asm volatile("s_waitcnt vmcnt(0)" ::: "memory");
;         } else {
;             XB_SPIN(xb_ld(&bar[XB_XGEN(b.x)]) == gen, bar);
;             __builtin_amdgcn_fence(__ATOMIC_ACQUIRE, "agent");
;             asm volatile("s_waitcnt vmcnt(0)" ::: "memory");
;         }
;     }
;     __syncthreads();
; }
.LBB0_942:
	s_waitcnt vmcnt(0)
	s_waitcnt lgkmcnt(0)
	s_barrier
	s_and_saveexec_b64 s[0:1], s[6:7]
	s_cbranch_execz .LBB0_990
	v_readlane_b32 s8, v254, 2
	v_readlane_b32 s9, v254, 3
	s_and_b32 s2, s88, 7
	s_lshl_b32 s2, s2, 8
	s_add_u32 s2, s8, s2
	s_addc_u32 s3, s9, 0
	v_mov_b32_e32 v0, 0
	v_mov_b32_e32 v1, 1
	v_mov_b32_e32 v5, 0x1400
	global_load_dwordx4 v[6:9], v0, s[8:9] offset:768 sc1
	global_load_dwordx4 v[10:13], v0, s[8:9] offset:784 sc1
	global_atomic_add v3, v5, v1, s[2:3] offset:128 sc0
	s_waitcnt vmcnt(0)
	v_add_u32_e32 v14, -1, v6
	v_and_b32_e32 v2, v14, v6
	v_add_u32_e32 v14, -1, v7
	v_and_or_b32 v2, v14, v7, v2
	v_add_u32_e32 v14, -1, v8
	v_and_or_b32 v2, v14, v8, v2
	v_add_u32_e32 v14, -1, v9
	v_and_or_b32 v2, v14, v9, v2
	v_add_u32_e32 v14, -1, v10
	v_and_or_b32 v2, v14, v10, v2
	v_add_u32_e32 v14, -1, v11
	v_and_or_b32 v2, v14, v11, v2
	v_add_u32_e32 v14, -1, v12
	v_and_or_b32 v2, v14, v12, v2
	v_add_u32_e32 v14, -1, v13
	v_and_or_b32 v2, v14, v13, v2
	v_cmp_ne_u32_e32 vcc, 0, v2
	s_cbranch_vccnz .Lmy_glob_k4
	v_and_b32_e32 v4, 0xffffffe0, v3
	v_add_u32_e32 v4, 32, v4
	v_add_u32_e32 v3, 1, v3
	v_cmp_eq_u32_e32 vcc, v3, v4
	s_cbranch_vccnz .Lmy_done_k4
	s_mov_b32 s10, 0

; __device__ __forceinline__ unsigned xb_ld(unsigned* p)              { return __hip_atomic_load(p, __ATOMIC_RELAXED, __HIP_MEMORY_SCOPE_AGENT); }
; __device__ __forceinline__ unsigned xb_add(unsigned* p, unsigned v) { return __hip_atomic_fetch_add(p, v, __ATOMIC_RELAXED, __HIP_MEMORY_SCOPE_AGENT); }
; #define XB_SPIN(cond, bar) do { unsigned _sp = 0; while (cond) { __builtin_amdgcn_s_sleep(1); \
;     if ((++_sp & 255u) == 0u) { if (xb_ld(&(bar)[XB_TMO])) break; if (_sp > XB_SPIN_CAP) { atomicAdd(&(bar)[XB_TMO], 1u); break; } } } } while (0)
; __device__ __forceinline__ void xcd_barrier(const XcdBarrier& b, bool leader) {
;     asm volatile("s_waitcnt vmcnt(0)" ::: "memory");
;     __syncthreads();
;     if (leader) {
;         unsigned* bar = b.bar;
;         __builtin_amdgcn_s_waitcnt(0);
;         unsigned nloc = b.st[0], nx = b.st[1];
;         if (nloc == 0u) { xcd_barrier_complete(bar, b.x, nloc, nx); b.st[0] = nloc; b.st[1] = nx; }
;         const unsigned old = xb_add(&bar[XB_XSUB(b.x)], 1u);
;         const unsigned gen = old / nloc;
;         if (old + 1u == (gen + 1u) * nloc) {
;             __builtin_amdgcn_fence(__ATOMIC_RELEASE, "agent");
;             asm volatile("s_waitcnt vmcnt(0)" ::: "memory");
;             const unsigned og = xb_add(&bar[XB_TOP], 1u);
;             const unsigned tg = og / nx;
;             if (og + 1u == (tg + 1u) * nx) xb_add(&bar[XB_TOPGEN], 1u);
;             else XB_SPIN(xb_ld(&bar[XB_TOPGEN]) == tg, bar);
;             __builtin_amdgcn_fence(__ATOMIC_ACQUIRE, "agent");
;             xb_add(&bar[XB_XGEN(b.x)], 1u);
;             asm volatile("s_waitcnt vmcnt(0)" ::: "memory");
;         } else {
;             XB_SPIN(xb_ld(&bar[XB_XGEN(b.x)]) == gen, bar);
;             __builtin_amdgcn_fence(__ATOMIC_ACQUIRE, "agent");
;             asm volatile("s_waitcnt vmcnt(0)" ::: "memory");
;         }
;     }
;     __syncthreads();
; }
.LBB0_1150:
	s_waitcnt vmcnt(0)
	s_waitcnt vmcnt(0) lgkmcnt(0)
	s_barrier
	s_and_saveexec_b64 s[0:1], s[6:7]
	s_cbranch_execz .LBB0_1198
	v_readlane_b32 s8, v254, 2
	v_readlane_b32 s9, v254, 3
	s_and_b32 s2, s88, 7
	s_lshl_b32 s2, s2, 8
	s_add_u32 s2, s8, s2
	s_addc_u32 s3, s9, 0
	v_mov_b32_e32 v0, 0
	v_mov_b32_e32 v1, 1
	v_mov_b32_e32 v5, 0x1400
	global_load_dwordx4 v[6:9], v0, s[8:9] offset:768 sc1
	global_load_dwordx4 v[10:13], v0, s[8:9] offset:784 sc1
	global_atomic_add v3, v5, v1, s[2:3] offset:128 sc0
	s_waitcnt vmcnt(0)
	v_add_u32_e32 v14, -1, v6
	v_and_b32_e32 v2, v14, v6
	v_add_u32_e32 v14, -1, v7
	v_and_or_b32 v2, v14, v7, v2
	v_add_u32_e32 v14, -1, v8
	v_and_or_b32 v2, v14, v8, v2
	v_add_u32_e32 v14, -1, v9
	v_and_or_b32 v2, v14, v9, v2
	v_add_u32_e32 v14, -1, v10
	v_and_or_b32 v2, v14, v10, v2
	v_add_u32_e32 v14, -1, v11
	v_and_or_b32 v2, v14, v11, v2
	v_add_u32_e32 v14, -1, v12
	v_and_or_b32 v2, v14, v12, v2
	v_add_u32_e32 v14, -1, v13
	v_and_or_b32 v2, v14, v13, v2
	v_cmp_ne_u32_e32 vcc, 0, v2
	s_cbranch_vccnz .Lmy_glob_k6
	v_and_b32_e32 v4, 0xffffffe0, v3
	v_add_u32_e32 v4, 32, v4
	v_add_u32_e32 v3, 1, v3
	v_cmp_eq_u32_e32 vcc, v3, v4
	s_cbranch_vccnz .Lmy_done_k6
	s_mov_b32 s10, 0

; __device__ __forceinline__ unsigned xb_ld(unsigned* p)              { return __hip_atomic_load(p, __ATOMIC_RELAXED, __HIP_MEMORY_SCOPE_AGENT); }
; __device__ __forceinline__ unsigned xb_add(unsigned* p, unsigned v) { return __hip_atomic_fetch_add(p, v, __ATOMIC_RELAXED, __HIP_MEMORY_SCOPE_AGENT); }
; #define XB_SPIN(cond, bar) do { unsigned _sp = 0; while (cond) { __builtin_amdgcn_s_sleep(1); \
;     if ((++_sp & 255u) == 0u) { if (xb_ld(&(bar)[XB_TMO])) break; if (_sp > XB_SPIN_CAP) { atomicAdd(&(bar)[XB_TMO], 1u); break; } } } } while (0)
; __device__ __forceinline__ void xcd_barrier(const XcdBarrier& b, bool leader) {
;     asm volatile("s_waitcnt vmcnt(0)" ::: "memory");
;     __syncthreads();
;     if (leader) {
;         unsigned* bar = b.bar;
;         __builtin_amdgcn_s_waitcnt(0);
;         unsigned nloc = b.st[0], nx = b.st[1];
;         if (nloc == 0u) { xcd_barrier_complete(bar, b.x, nloc, nx); b.st[0] = nloc; b.st[1] = nx; }
;         const unsigned old = xb_add(&bar[XB_XSUB(b.x)], 1u);
;         const unsigned gen = old / nloc;
;         if (old + 1u == (gen + 1u) * nloc) {
;             __builtin_amdgcn_fence(__ATOMIC_RELEASE, "agent");
;             asm volatile("s_waitcnt vmcnt(0)" ::: "memory");
;             const unsigned og = xb_add(&bar[XB_TOP], 1u);
;             const unsigned tg = og / nx;
;             if (og + 1u == (tg + 1u) * nx) xb_add(&bar[XB_TOPGEN], 1u);
;             else XB_SPIN(xb_ld(&bar[XB_TOPGEN]) == tg, bar);
;             __builtin_amdgcn_fence(__ATOMIC_ACQUIRE, "agent");
;             xb_add(&bar[XB_XGEN(b.x)], 1u);
;             asm volatile("s_waitcnt vmcnt(0)" ::: "memory");
;         } else {
;             XB_SPIN(xb_ld(&bar[XB_XGEN(b.x)]) == gen, bar);
;             __builtin_amdgcn_fence(__ATOMIC_ACQUIRE, "agent");
;             asm volatile("s_waitcnt vmcnt(0)" ::: "memory");
;         }
;     }
;     __syncthreads();
; }
.LBB0_1391:
	s_waitcnt vmcnt(0)
	s_waitcnt vmcnt(0) lgkmcnt(0)
	s_barrier
	s_and_saveexec_b64 s[4:5], s[6:7]
	s_cbranch_execz .LBB0_1439
	v_readlane_b32 s8, v254, 2
	v_readlane_b32 s9, v254, 3
	s_and_b32 s2, s88, 7
	s_lshl_b32 s2, s2, 8
	s_add_u32 s2, s8, s2
	s_addc_u32 s3, s9, 0
	v_mov_b32_e32 v0, 0
	v_mov_b32_e32 v1, 1
	v_mov_b32_e32 v5, 0x1400
	global_load_dwordx4 v[6:9], v0, s[8:9] offset:768 sc1
	global_load_dwordx4 v[10:13], v0, s[8:9] offset:784 sc1
	global_atomic_add v3, v5, v1, s[2:3] offset:128 sc0
	s_waitcnt vmcnt(0)
	v_add_u32_e32 v14, -1, v6
	v_and_b32_e32 v2, v14, v6
	v_add_u32_e32 v14, -1, v7
	v_and_or_b32 v2, v14, v7, v2
	v_add_u32_e32 v14, -1, v8
	v_and_or_b32 v2, v14, v8, v2
	v_add_u32_e32 v14, -1, v9
	v_and_or_b32 v2, v14, v9, v2
	v_add_u32_e32 v14, -1, v10
	v_and_or_b32 v2, v14, v10, v2
	v_add_u32_e32 v14, -1, v11
	v_and_or_b32 v2, v14, v11, v2
	v_add_u32_e32 v14, -1, v12
	v_and_or_b32 v2, v14, v12, v2
	v_add_u32_e32 v14, -1, v13
	v_and_or_b32 v2, v14, v13, v2
	v_cmp_ne_u32_e32 vcc, 0, v2
	s_cbranch_vccnz .Lmy_glob_k8
	v_and_b32_e32 v4, 0xffffffe0, v3
	v_add_u32_e32 v4, 32, v4
	v_add_u32_e32 v3, 1, v3
	v_cmp_eq_u32_e32 vcc, v3, v4
	s_cbranch_vccnz .Lmy_done_k8
	s_mov_b32 s10, 0

; #define PH(k) (IN(k) && ((MK_MASK >> (k)) & 1))
; #define REPS(k) for (int rep_ = 0; rep_ < (((MK_REP_MASK) >> (k)) & 1) + 1; ++rep_)
;     __host__ __device__ __forceinline__ bool next(int i, Unit& u) const {
;         const long L = (long)i * G + c; if (L >= nwg) return false;
;         int wgid = (int)L; { const int q = nwg / NXCD, r = nwg % NXCD, xcd = wgid % NXCD, off = wgid / NXCD; wgid = (xcd < r ? xcd * (q + 1) : r * (q + 1) + (xcd - r) * q) + off; }
;         const int nig = WGM * nN, gid = wgid / nig, fm = gid * WGM, gsz = (nM - fm) < WGM ? (nM - fm) : WGM;
;         u.pm = fm + ((wgid % nig) % gsz); u.pn = (wgid % nig) / gsz; if (rev) u.pm = nM - 1 - u.pm; return true;
; __global__ void __launch_bounds__(NWAVES * 64, 2) mk_fwd(Params P) {
;     ...
;     if (PH(9)) REPS(9) { pg8::Gemm g{ZH, Wdn_t, M, D, FF}; pg8::StaticOrder S; S.init(M, D, G, bx); S.rev = true;
;         pg8::EpiRes2<true, true> E{H2B, H1B  , SS3};
;         pg8::gemm_phase<pg8::EpiRes2<true, true>, pg8::StaticOrder, true, true>(lds, g, S, E, wave); }
.LBB0_1440:
	s_cmp_lt_i32 s74, 10
	s_cselect_b64 s[2:3], -1, 0
	s_and_b64 s[0:1], s[2:3], s[0:1]
	s_andn2_b64 vcc, exec, s[0:1]
	s_cbranch_vccnz .LBB0_1479
	v_and_b32_e32 v248, 15, v212
	v_lshrrev_b32_e32 v249, 2, v212
	v_sub_u32_e32 v249, v249, v248
	v_lshrrev_b32_e32 v248, 4, v212
	v_and_b32_e32 v253, 3, v212
	v_sub_u32_e32 v248, v253, v248
	v_lshlrev_b32_e32 v248, 4, v248
	v_mul_i32_i24_e32 v250, 0x800, v249
	v_add_u32_e32 v250, v250, v248
	v_ashrrev_i32_e32 v251, 31, v250
	v_lshlrev_b32_e32 v253, 4, v253
	v_lshrrev_b32_e32 v248, 2, v212
	v_add_u32_e32 v253, v253, v248
	v_lshlrev_b32_e32 v253, 2, v253
	s_and_b32 s2, s93, 0xffffffc0
	v_mov_b32_e32 v8, v212
	s_cmpk_lt_i32 s88, 0x200
	s_cselect_b64 s[4:5], -1, 0
	v_add_u32_e32 v0, s2, v8
	s_cmpk_gt_i32 s88, 0x1ff
	v_readfirstlane_b32 s6, v0
	s_cbranch_scc1 .LBB0_1443
	s_ashr_i32 s2, s88, 31
	s_lshr_b32 s2, s2, 29
	s_add_i32 s2, s88, s2
	s_ashr_i32 s3, s2, 3
	s_and_b32 s2, s2, -8
	s_sub_i32 s2, s88, s2
	s_lshl_b32 s8, s2, 6
	s_mul_i32 s7, s2, 0x41
	s_cmp_lt_i32 s2, 0
	s_cselect_b32 s2, s7, s8
	s_add_i32 s2, s2, s3
	s_ashr_i32 s3, s2, 31
	s_lshr_b32 s3, s3, 27
	s_add_i32 s3, s2, s3
	s_ashr_i32 s7, s3, 5
	s_andn2_b32 s3, s3, 31
	s_sub_i32 s2, s2, s3
	s_bfe_i32 s3, s2, 0x80000
	s_bfe_u32 s3, s3, 0x3000c
	s_add_i32 s3, s2, s3
	s_bfe_i32 s8, s3, 0x80000
	s_and_b32 s3, s3, 0xf8
	s_sub_i32 s2, s3, s2
	s_sext_i32_i8 s2, s2
	s_lshl_b32 s3, s7, 3
	s_sext_i32_i16 s8, s8
	s_sub_i32 s2, s2, s3
	s_ashr_i32 s8, s8, 3
	s_add_i32 s34, s2, 0x7f
	s_xor_b32 s34, s34, 0x70

;     __host__ __device__ __forceinline__ bool next(int i, Unit& u) const {
;         const long L = (long)i * G + c; if (L >= nwg) return false;
;         int wgid = (int)L; { const int q = nwg / NXCD, r = nwg % NXCD, xcd = wgid % NXCD, off = wgid / NXCD; wgid = (xcd < r ? xcd * (q + 1) : r * (q + 1) + (xcd - r) * q) + off; }
;         const int nig = WGM * nN, gid = wgid / nig, fm = gid * WGM, gsz = (nM - fm) < WGM ? (nM - fm) : WGM;
;         u.pm = fm + ((wgid % nig) % gsz); u.pn = (wgid % nig) / gsz; if (rev) u.pm = nM - 1 - u.pm; return true;
.LBB0_1454:
	s_ashr_i32 s24, s26, 3
	s_add_i32 s24, s28, s24
	s_ashr_i32 s25, s24, 31
	s_lshr_b32 s25, s25, 27
	s_add_i32 s25, s24, s25
	s_ashr_i32 s26, s25, 5
	s_lshl_b32 s26, s26, 3
	s_sub_i32 s27, 0x80, s26
	s_min_i32 s27, s27, 8
	s_abs_i32 s28, s27
	v_cvt_f32_u32_e32 v0, s28
	s_sub_i32 s30, 0, s28
	s_andn2_b32 s25, s25, 31
	s_sub_i32 s25, s24, s25
	v_rcp_iflag_f32_e32 v0, v0
	s_abs_i32 s24, s25
	s_xor_b32 s29, s25, s27
	s_ashr_i32 s29, s29, 31
	v_mul_f32_e32 v0, 0x4f7ffffe, v0
	v_cvt_u32_f32_e32 v0, v0
	s_nop 0
	v_readfirstlane_b32 s31, v0
	s_mul_i32 s30, s30, s31
	s_mul_hi_u32 s30, s31, s30
	s_add_i32 s31, s31, s30
	s_mul_hi_u32 s30, s24, s31
	s_mul_i32 s31, s30, s28
	s_sub_i32 s24, s24, s31
	s_add_i32 s35, s30, 1
	s_sub_i32 s31, s24, s28
	s_cmp_ge_u32 s24, s28
	s_cselect_b32 s30, s35, s30
	s_cselect_b32 s24, s31, s24
	s_add_i32 s31, s30, 1
	s_cmp_ge_u32 s24, s28
	s_cselect_b32 s24, s31, s30
	s_xor_b32 s24, s24, s29
	s_sub_i32 s24, s24, s29
	s_mul_i32 s27, s24, s27
	s_sub_i32 s25, s25, s27
	s_add_i32 s25, s25, s26
	s_sub_i32 s26, 0x7f, s25
	s_xor_b32 s26, s26, 0x70

; __device__ __forceinline__ unsigned xb_ld(unsigned* p)              { return __hip_atomic_load(p, __ATOMIC_RELAXED, __HIP_MEMORY_SCOPE_AGENT); }
; __device__ __forceinline__ unsigned xb_add(unsigned* p, unsigned v) { return __hip_atomic_fetch_add(p, v, __ATOMIC_RELAXED, __HIP_MEMORY_SCOPE_AGENT); }
; #define XB_SPIN(cond, bar) do { unsigned _sp = 0; while (cond) { __builtin_amdgcn_s_sleep(1); \
;     if ((++_sp & 255u) == 0u) { if (xb_ld(&(bar)[XB_TMO])) break; if (_sp > XB_SPIN_CAP) { atomicAdd(&(bar)[XB_TMO], 1u); break; } } } } while (0)
; __device__ __forceinline__ void xcd_barrier(const XcdBarrier& b, bool leader) {
;     asm volatile("s_waitcnt vmcnt(0)" ::: "memory");
;     __syncthreads();
;     if (leader) {
;         unsigned* bar = b.bar;
;         __builtin_amdgcn_s_waitcnt(0);
;         unsigned nloc = b.st[0], nx = b.st[1];
;         if (nloc == 0u) { xcd_barrier_complete(bar, b.x, nloc, nx); b.st[0] = nloc; b.st[1] = nx; }
;         const unsigned old = xb_add(&bar[XB_XSUB(b.x)], 1u);
;         const unsigned gen = old / nloc;
;         if (old + 1u == (gen + 1u) * nloc) {
;             __builtin_amdgcn_fence(__ATOMIC_RELEASE, "agent");
;             asm volatile("s_waitcnt vmcnt(0)" ::: "memory");
;             const unsigned og = xb_add(&bar[XB_TOP], 1u);
;             const unsigned tg = og / nx;
;             if (og + 1u == (tg + 1u) * nx) xb_add(&bar[XB_TOPGEN], 1u);
;             else XB_SPIN(xb_ld(&bar[XB_TOPGEN]) == tg, bar);
;             __builtin_amdgcn_fence(__ATOMIC_ACQUIRE, "agent");
;             xb_add(&bar[XB_XGEN(b.x)], 1u);
;             asm volatile("s_waitcnt vmcnt(0)" ::: "memory");
;         } else {
;             XB_SPIN(xb_ld(&bar[XB_XGEN(b.x)]) == gen, bar);
;             __builtin_amdgcn_fence(__ATOMIC_ACQUIRE, "agent");
;             asm volatile("s_waitcnt vmcnt(0)" ::: "memory");
;         }
;     }
;     __syncthreads();
; }
.Lmy_glob_k9:
	s_add_i32 s2, 0, 0x20400
	v_mov_b32_e32 v0, s2
	s_waitcnt vmcnt(0) expcnt(0) lgkmcnt(0)
	ds_read_b32 v2, v0
	s_add_i32 s2, 0, 0x20404
	v_mov_b32_e32 v0, s2
	ds_read_b32 v0, v0
	s_waitcnt lgkmcnt(1)
	v_cmp_ne_u32_e32 vcc, 0, v2
	s_cbranch_vccnz .LBB0_1498
	v_readlane_b32 s6, v254, 0
	v_readlane_b32 s7, v254, 1
	s_load_dwordx2 s[2:3], s[6:7], 0x4
	s_add_u32 s6, s72, 0x310200
	s_addc_u32 s7, s73, 0
	s_add_u32 s8, s72, 0x310400
	s_addc_u32 s9, s73, 0
	s_add_u32 s10, s72, 0x310500
	s_addc_u32 s11, s73, 0
	s_add_u32 s12, s72, 0x310600
	s_addc_u32 s13, s73, 0
	s_add_u32 s14, s72, 0x310700
	s_addc_u32 s15, s73, 0
	s_add_u32 s16, s72, 0x310800
	s_addc_u32 s17, s73, 0
	s_add_u32 s18, s72, 0x310900
	s_addc_u32 s19, s73, 0
	s_add_u32 s20, s72, 0x310a00
	s_addc_u32 s21, s73, 0
	s_add_u32 s22, s72, 0x310b00
	s_addc_u32 s23, s73, 0
	s_add_u32 s24, s72, 0x310c00
	s_addc_u32 s25, s73, 0
	s_add_u32 s26, s72, 0x310d00
	s_addc_u32 s27, s73, 0
	s_add_u32 s28, s72, 0x310e00
	s_addc_u32 s29, s73, 0
	s_add_u32 s30, s72, 0x310f00
	s_addc_u32 s31, s73, 0
	s_add_u32 s34, s72, 0x311000
	s_addc_u32 s35, s73, 0
	s_add_u32 s36, s72, 0x311100
	s_addc_u32 s37, s73, 0
	s_add_u32 s38, s72, 0x311200
	s_addc_u32 s39, s73, 0
	s_waitcnt lgkmcnt(0)
	s_mul_i32 s2, s2, s82
	s_add_u32 s40, s72, 0x311300
	s_mul_i32 s2, s2, s3
	s_addc_u32 s41, s73, 0
	s_mov_b32 s3, 1
	v_mov_b32_e32 v16, 0
	s_branch .LBB0_1486
